# grid barrier: last arriver no longer bumps the (now unpolled) top generation word before its acquire
# baseline (speedup 1.0000x reference)
; DI unsigned xb_ld(unsigned* p) { return __hip_atomic_load(p, __ATOMIC_RELAXED, __HIP_MEMORY_SCOPE_AGENT); }
; DI unsigned xb_add(unsigned* p, unsigned v) { return __hip_atomic_fetch_add(p, v, __ATOMIC_RELAXED, __HIP_MEMORY_SCOPE_AGENT); }
; #define XB_SPIN(cond, bar) do { unsigned _sp = 0; while (cond) { __builtin_amdgcn_s_sleep(1); \
;     if ((++_sp & 255u) == 0u) { if (xb_ld(&(bar)[XB_TMO])) break; if (_sp > XB_SPIN_CAP) { atomicAdd(&(bar)[XB_TMO], 1u); break; } } } } while (0)
; DI void xcd_barrier(const XcdBarrier& b) {
;     ...
;     const unsigned old = xb_add(&bar[XB_XSUB(b.x)], 1u);
;     const unsigned gen = old / nloc;
;     if (old + 1u == (gen + 1u) * nloc) {
;       __builtin_amdgcn_fence(__ATOMIC_RELEASE, "agent");
;       asm volatile("s_waitcnt vmcnt(0)" ::: "memory");
;       const unsigned og = xb_add(&bar[XB_TOP], 1u);
;       const unsigned tg = og / nx;
;       if (og + 1u == (tg + 1u) * nx) xb_add(&bar[XB_TOPGEN], 1u);
;       else XB_SPIN(xb_ld(&bar[XB_TOPGEN]) == tg, bar);
.LBB0_89:
	s_or_b64 exec, exec, s[6:7]
	v_cvt_f32_u32_e32 v3, v0
	s_waitcnt vmcnt(0)
	v_readfirstlane_b32 s3, v2
	s_mov_b64 s[6:7], 0
	v_rcp_iflag_f32_e32 v3, v3
	v_add_u32_e32 v1, s3, v1
	v_add_u32_e32 v4, 1, v1
	v_mul_f32_e32 v2, 0x4f7ffffe, v3
	v_cvt_u32_f32_e32 v2, v2
	v_sub_u32_e32 v3, 0, v0
	v_mul_lo_u32 v3, v3, v2
	v_mul_hi_u32 v3, v2, v3
	v_add_u32_e32 v2, v2, v3
	v_mul_hi_u32 v2, v1, v2
	v_mul_lo_u32 v3, v2, v0
	v_sub_u32_e32 v1, v1, v3
	v_add_u32_e32 v5, 1, v2
	v_cmp_ge_u32_e32 vcc, v1, v0
	v_sub_u32_e32 v3, v1, v0
	s_nop 0
	v_cndmask_b32_e32 v2, v2, v5, vcc
	v_cndmask_b32_e32 v1, v1, v3, vcc
	v_add_u32_e32 v3, 1, v2
	v_cmp_ge_u32_e32 vcc, v1, v0
	s_nop 1
	v_cndmask_b32_e32 v2, v2, v3, vcc
	v_mad_u64_u32 v[0:1], s[4:5], v0, v2, v[0:1]
	v_readlane_b32 s4, v251, 57
	v_readlane_b32 s5, v251, 58
	v_cmp_ne_u32_e32 vcc, v4, v0
	v_mov_b32_e32 v5, v0
	s_nop 0
	v_mov_b64_e32 v[0:1], s[4:5]
	s_and_saveexec_b64 s[4:5], vcc
	s_cbranch_execz .LBB0_101
	v_readlane_b32 s6, v251, 55
	v_mov_b32_e32 v0, 0
	v_readlane_b32 s7, v251, 56
	s_mov_b64 s[8:9], 0
	s_nop 3
	global_load_dword v1, v0, s[6:7] sc1
	s_waitcnt vmcnt(0)
	v_cmp_lt_u32_e32 vcc, v1, v5
	s_and_saveexec_b64 s[6:7], vcc
	s_cbranch_execz .LBB0_100
	s_mov_b32 s3, 1
	s_branch .LBB0_93

; DI unsigned xb_ld(unsigned* p) { return __hip_atomic_load(p, __ATOMIC_RELAXED, __HIP_MEMORY_SCOPE_AGENT); }
; DI unsigned xb_add(unsigned* p, unsigned v) { return __hip_atomic_fetch_add(p, v, __ATOMIC_RELAXED, __HIP_MEMORY_SCOPE_AGENT); }
; #define XB_SPIN(cond, bar) do { unsigned _sp = 0; while (cond) { __builtin_amdgcn_s_sleep(1); \
;     if ((++_sp & 255u) == 0u) { if (xb_ld(&(bar)[XB_TMO])) break; if (_sp > XB_SPIN_CAP) { atomicAdd(&(bar)[XB_TMO], 1u); break; } } } } while (0)
; DI void xcd_barrier(const XcdBarrier& b) {
;     ...
;     const unsigned old = xb_add(&bar[XB_XSUB(b.x)], 1u);
;     const unsigned gen = old / nloc;
;     if (old + 1u == (gen + 1u) * nloc) {
;       __builtin_amdgcn_fence(__ATOMIC_RELEASE, "agent");
;       asm volatile("s_waitcnt vmcnt(0)" ::: "memory");
;       const unsigned og = xb_add(&bar[XB_TOP], 1u);
;       const unsigned tg = og / nx;
;       if (og + 1u == (tg + 1u) * nx) xb_add(&bar[XB_TOPGEN], 1u);
;       else XB_SPIN(xb_ld(&bar[XB_TOPGEN]) == tg, bar);
.LBB0_176:
	s_or_b64 exec, exec, s[4:5]
	s_waitcnt vmcnt(0)
	v_readfirstlane_b32 s2, v3
	v_cvt_f32_u32_e32 v3, v0
	v_sub_u32_e32 v4, 0, v0
	v_add_u32_e32 v2, s2, v2
	s_mov_b64 s[4:5], 0
	v_rcp_iflag_f32_e32 v3, v3
	s_nop 0
	v_mul_f32_e32 v3, 0x4f7ffffe, v3
	v_cvt_u32_f32_e32 v3, v3
	v_mul_lo_u32 v4, v4, v3
	v_mul_hi_u32 v4, v3, v4
	v_add_u32_e32 v3, v3, v4
	v_mul_hi_u32 v3, v2, v3
	v_mul_lo_u32 v4, v3, v0
	v_sub_u32_e32 v4, v2, v4
	v_cmp_ge_u32_e32 vcc, v4, v0
	v_add_u32_e32 v5, 1, v3
	s_nop 0
	v_cndmask_b32_e32 v3, v3, v5, vcc
	v_sub_u32_e32 v5, v4, v0
	v_cndmask_b32_e32 v4, v4, v5, vcc
	v_cmp_ge_u32_e32 vcc, v4, v0
	v_add_u32_e32 v4, 1, v3
	v_add_u32_e32 v5, 1, v2
	v_cndmask_b32_e32 v4, v3, v4, vcc
	v_mad_u64_u32 v[2:3], s[2:3], v0, v4, v[0:1]
	v_readlane_b32 s2, v251, 57
	v_readlane_b32 s3, v251, 58
	v_cmp_ne_u32_e32 vcc, v5, v2
	v_mov_b32_e32 v5, v2
	s_nop 0
	v_mov_b64_e32 v[2:3], s[2:3]
	s_and_saveexec_b64 s[2:3], vcc
	s_cbranch_execz .LBB0_188
	v_readlane_b32 s4, v251, 55
	v_readlane_b32 s5, v251, 56
	s_mov_b64 s[6:7], 0
	s_nop 3
	global_load_dword v0, v1, s[4:5] sc1
	s_waitcnt vmcnt(0)
	v_cmp_lt_u32_e32 vcc, v0, v5
	s_and_saveexec_b64 s[4:5], vcc
	s_cbranch_execz .LBB0_187
	s_mov_b32 s38, 1
	s_branch .LBB0_180

; DI unsigned xb_ld(unsigned* p) { return __hip_atomic_load(p, __ATOMIC_RELAXED, __HIP_MEMORY_SCOPE_AGENT); }
; DI unsigned xb_add(unsigned* p, unsigned v) { return __hip_atomic_fetch_add(p, v, __ATOMIC_RELAXED, __HIP_MEMORY_SCOPE_AGENT); }
; #define XB_SPIN(cond, bar) do { unsigned _sp = 0; while (cond) { __builtin_amdgcn_s_sleep(1); \
;     if ((++_sp & 255u) == 0u) { if (xb_ld(&(bar)[XB_TMO])) break; if (_sp > XB_SPIN_CAP) { atomicAdd(&(bar)[XB_TMO], 1u); break; } } } } while (0)
; DI void xcd_barrier(const XcdBarrier& b) {
;     ...
;     const unsigned old = xb_add(&bar[XB_XSUB(b.x)], 1u);
;     const unsigned gen = old / nloc;
;     if (old + 1u == (gen + 1u) * nloc) {
;       __builtin_amdgcn_fence(__ATOMIC_RELEASE, "agent");
;       asm volatile("s_waitcnt vmcnt(0)" ::: "memory");
;       const unsigned og = xb_add(&bar[XB_TOP], 1u);
;       const unsigned tg = og / nx;
;       if (og + 1u == (tg + 1u) * nx) xb_add(&bar[XB_TOPGEN], 1u);
;       else XB_SPIN(xb_ld(&bar[XB_TOPGEN]) == tg, bar);
.LBB0_375:
	s_or_b64 exec, exec, s[4:5]
	s_waitcnt vmcnt(0)
	v_readfirstlane_b32 s2, v3
	v_cvt_f32_u32_e32 v3, v0
	v_sub_u32_e32 v4, 0, v0
	v_add_u32_e32 v2, s2, v2
	s_mov_b64 s[4:5], 0
	v_rcp_iflag_f32_e32 v3, v3
	s_nop 0
	v_mul_f32_e32 v3, 0x4f7ffffe, v3
	v_cvt_u32_f32_e32 v3, v3
	v_mul_lo_u32 v4, v4, v3
	v_mul_hi_u32 v4, v3, v4
	v_add_u32_e32 v3, v3, v4
	v_mul_hi_u32 v3, v2, v3
	v_mul_lo_u32 v4, v3, v0
	v_sub_u32_e32 v4, v2, v4
	v_cmp_ge_u32_e32 vcc, v4, v0
	v_add_u32_e32 v5, 1, v3
	s_nop 0
	v_cndmask_b32_e32 v3, v3, v5, vcc
	v_sub_u32_e32 v5, v4, v0
	v_cndmask_b32_e32 v4, v4, v5, vcc
	v_cmp_ge_u32_e32 vcc, v4, v0
	v_add_u32_e32 v4, 1, v3
	v_add_u32_e32 v5, 1, v2
	v_cndmask_b32_e32 v4, v3, v4, vcc
	v_mad_u64_u32 v[2:3], s[2:3], v0, v4, v[0:1]
	v_readlane_b32 s2, v251, 57
	v_readlane_b32 s3, v251, 58
	v_cmp_ne_u32_e32 vcc, v5, v2
	v_mov_b32_e32 v5, v2
	s_nop 0
	v_mov_b64_e32 v[2:3], s[2:3]
	s_and_saveexec_b64 s[2:3], vcc
	s_cbranch_execz .LBB0_387
	v_readlane_b32 s4, v251, 55
	v_readlane_b32 s5, v251, 56
	s_mov_b64 s[6:7], 0
	s_nop 3
	global_load_dword v0, v1, s[4:5] sc1
	s_waitcnt vmcnt(0)
	v_cmp_lt_u32_e32 vcc, v0, v5
	s_and_saveexec_b64 s[4:5], vcc
	s_cbranch_execz .LBB0_386
	s_mov_b32 s40, 1
	s_branch .LBB0_379
